# hand-written gated short-conv item: 8 consecutive tokens per wave, all loads up front, scalar branches
# speedup vs baseline: 1.0132x; 1.0052x over previous
; __device__ void conv_item(const Params& p, int it) {
;   const int cg = threadIdx.x & 63, tl = threadIdx.x >> 6;
;   const int c0 = cg * 8;
;   float w0[8], w1[8], w2[8];
; #pragma unroll
;   for (int j = 0; j < 8; ++j) { w0[j] = p.conv_w[c0 + j]; w1[j] = p.conv_w[512 + c0 + j]; w2[j] = p.conv_w[1024 + c0 + j]; }
; #pragma unroll 2
;   for (int k = 0; k < 8; ++k) {
;     const int tok = it * 64 + k * 8 + tl;
;     const size_t o = (size_t)tok * 512 + c0;
;     float u0[8], u1[8], u2[8], bg[8], gt[8], a[8], b[8];
;     unpack8(*reinterpret_cast<const u32x4*>(p.Cb + o), a);
;     unpack8(*reinterpret_cast<const u32x4*>(p.Hb + o), b);
; #pragma unroll
;     for (int j = 0; j < 8; ++j) u0[j] = a[j] * b[j];
;     const bool prompt = tok < NPROMPT;
;     const int s = prompt ? (tok & (SEQ - 1)) : ((tok - NPROMPT) & 15);
;     const int sb = prompt ? 0 : ((tok - NPROMPT) >> 4);
;     if (s >= 1) {
;       unpack8(*reinterpret_cast<const u32x4*>(p.Cb + o - 512), a);
;       unpack8(*reinterpret_cast<const u32x4*>(p.Hb + o - 512), b);
; #pragma unroll
;       for (int j = 0; j < 8; ++j) u1[j] = a[j] * b[j];
;     } else {
; #pragma unroll
;       for (int j = 0; j < 8; ++j) u1[j] = prompt ? 0.f : p.cache_conv[(size_t)(sb * 2 + 1) * 512 + c0 + j];
;     }
;     if (s >= 2) {
;       unpack8(*reinterpret_cast<const u32x4*>(p.Cb + o - 1024), a);
;       unpack8(*reinterpret_cast<const u32x4*>(p.Hb + o - 1024), b);
; #pragma unroll
;       for (int j = 0; j < 8; ++j) u2[j] = a[j] * b[j];
;     } else {
; #pragma unroll
;       for (int j = 0; j < 8; ++j) u2[j] = prompt ? 0.f : p.cache_conv[(size_t)(sb * 2 + s) * 512 + c0 + j];
;     }
;     unpack8(*reinterpret_cast<const u32x4*>(p.Bb + o), bg);
;     unpack8(*reinterpret_cast<const u32x4*>(p.Gb + (size_t)tok * 2048 + 1024 + c0), gt);
.LBB0_409:
	s_or_b64 exec, exec, s[8:9]
	s_waitcnt lgkmcnt(0)
	s_barrier
	s_waitcnt vmcnt(0)
	ds_read_b32 v0, v197
	s_movk_i32 s8, 0x587
	s_waitcnt lgkmcnt(0)
	s_barrier
	v_cmp_lt_i32_e32 vcc, s8, v0
	v_readfirstlane_b32 s2, v0
	s_mov_b64 s[8:9], -1
	s_cbranch_vccnz .LBB0_404
	s_cmpk_gt_i32 s2, 0xff
	s_cbranch_scc0 .LBB0_525
	s_cmpk_gt_u32 s2, 0x2ff
	s_cbranch_scc0 .LBB0_520
	s_cmpk_gt_u32 s2, 0x37f
	s_cbranch_scc0 .LBB0_516
	global_load_dwordx4 v[0:3], v[166:167], off offset:16
	global_load_dwordx4 v[4:7], v[166:167], off
	global_load_dwordx4 v[8:11], v[166:167], off offset:2064
	global_load_dwordx4 v[12:15], v[166:167], off offset:2048
	global_load_dwordx4 v[16:19], v[168:169], off offset:16
	global_load_dwordx4 v[20:23], v[168:169], off
	s_add_i32 s8, s2, 0xfffffc80
	s_lshl_b32 s8, s8, 6
	v_lshl_add_u32 v248, v192, 3, s8
	s_mov_b64 s[10:11], 0x1000
	v_lshlrev_b32_e32 v250, 10, v248
	v_lshl_add_u32 v250, v162, 1, v250
	v_add_u32_e32 v250, 0xfffff800, v250
	v_ashrrev_i32_e32 v251, 31, v250
	v_readfirstlane_b32 s9, v248
	v_lshl_add_u64 v[252:253], v[250:251], 0, s[76:77]
	global_load_dwordx4 v[24:27], v[252:253], off
	global_load_dwordx4 v[28:31], v[252:253], off offset:1024
	global_load_dwordx4 v[32:35], v[252:253], off offset:2048
	global_load_dwordx4 v[36:39], v[252:253], off offset:3072
	v_lshl_add_u64 v[252:253], v[252:253], 0, s[10:11]
	global_load_dwordx4 v[40:43], v[252:253], off
	global_load_dwordx4 v[44:47], v[252:253], off offset:1024
	global_load_dwordx4 v[48:51], v[252:253], off offset:2048
	global_load_dwordx4 v[52:55], v[252:253], off offset:3072
	v_lshl_add_u64 v[252:253], v[252:253], 0, s[10:11]
	global_load_dwordx4 v[56:59], v[252:253], off
	global_load_dwordx4 v[60:63], v[252:253], off offset:1024
	v_lshl_add_u64 v[252:253], v[250:251], 0, s[72:73]
	global_load_dwordx4 v[64:67], v[252:253], off
	global_load_dwordx4 v[68:71], v[252:253], off offset:1024
	global_load_dwordx4 v[72:75], v[252:253], off offset:2048
	global_load_dwordx4 v[76:79], v[252:253], off offset:3072
	v_lshl_add_u64 v[252:253], v[252:253], 0, s[10:11]
	global_load_dwordx4 v[80:83], v[252:253], off
	global_load_dwordx4 v[84:87], v[252:253], off offset:1024
	global_load_dwordx4 v[88:91], v[252:253], off offset:2048
	global_load_dwordx4 v[92:95], v[252:253], off offset:3072
	v_lshl_add_u64 v[252:253], v[252:253], 0, s[10:11]
	global_load_dwordx4 v[96:99], v[252:253], off
	global_load_dwordx4 v[100:103], v[252:253], off offset:1024
	v_lshl_add_u64 v[252:253], v[250:251], 0, s[74:75]
	global_load_dwordx4 v[104:107], v[252:253], off offset:2048
	global_load_dwordx4 v[108:111], v[252:253], off offset:3072
	v_lshl_add_u64 v[252:253], v[252:253], 0, s[10:11]
	global_load_dwordx4 v[112:115], v[252:253], off
	global_load_dwordx4 v[116:119], v[252:253], off offset:1024
	global_load_dwordx4 v[120:123], v[252:253], off offset:2048
	global_load_dwordx4 v[124:127], v[252:253], off offset:3072
	v_lshl_add_u64 v[252:253], v[252:253], 0, s[10:11]
	global_load_dwordx4 v[128:131], v[252:253], off
	global_load_dwordx4 v[132:135], v[252:253], off offset:1024
	v_lshlrev_b32_e32 v246, 12, v248
	v_mov_b32_e32 v247, 0
	v_lshl_add_u64 v[252:253], v[176:177], 0, v[246:247]
	global_load_dwordx4 v[200:203], v[252:253], off offset:2048
	v_lshl_add_u64 v[252:253], v[252:253], 0, s[10:11]
	global_load_dwordx4 v[204:207], v[252:253], off offset:2048
	v_lshl_add_u64 v[252:253], v[252:253], 0, s[10:11]
	global_load_dwordx4 v[208:211], v[252:253], off offset:2048
	v_lshl_add_u64 v[252:253], v[252:253], 0, s[10:11]
	global_load_dwordx4 v[212:215], v[252:253], off offset:2048
	v_lshl_add_u64 v[252:253], v[252:253], 0, s[10:11]
	global_load_dwordx4 v[216:219], v[252:253], off offset:2048
	v_lshl_add_u64 v[252:253], v[252:253], 0, s[10:11]
	global_load_dwordx4 v[220:223], v[252:253], off offset:2048
	v_lshl_add_u64 v[252:253], v[252:253], 0, s[10:11]
	global_load_dwordx4 v[224:227], v[252:253], off offset:2048
	v_lshl_add_u64 v[252:253], v[252:253], 0, s[10:11]
	global_load_dwordx4 v[228:231], v[252:253], off offset:2048
	s_cmp_lt_u32 s9, 0x8000
	s_cbranch_scc0 .Lcv_sample
	s_and_b32 s12, s9, 0x3fff
	s_cmp_eq_u32 s12, 0
	s_cbranch_scc0 .Lcv_normal
	v_mov_b32_e32 v136, 0
	v_mov_b32_e32 v137, 0
	v_mov_b32_e32 v138, 0
	v_mov_b32_e32 v139, 0
	v_mov_b32_e32 v140, 0
	v_mov_b32_e32 v141, 0
	v_mov_b32_e32 v142, 0
	v_mov_b32_e32 v143, 0
	v_mov_b32_e32 v144, 0
	v_mov_b32_e32 v145, 0
	v_mov_b32_e32 v146, 0
	v_mov_b32_e32 v147, 0
	v_mov_b32_e32 v148, 0
	v_mov_b32_e32 v149, 0
	v_mov_b32_e32 v150, 0
	v_mov_b32_e32 v151, 0
	s_waitcnt vmcnt(16)
	s_branch .Lcv_tokens
.Lcv_sample:
	s_sub_i32 s12, s9, 0x8000
	s_and_b32 s13, s12, 15
	s_cmp_eq_u32 s13, 0
	s_cbranch_scc0 .Lcv_normal
	s_lshr_b32 s12, s12, 4
	s_lshl_b32 s12, s12, 12
	s_mov_b32 s13, 0
	v_lshl_add_u64 v[252:253], v[170:171], 0, s[12:13]
	global_load_dwordx4 v[136:139], v[252:253], off
	global_load_dwordx4 v[140:143], v[252:253], off offset:16
	global_load_dwordx4 v[144:147], v[252:253], off offset:2048
	global_load_dwordx4 v[148:151], v[252:253], off offset:2064
	s_waitcnt vmcnt(0)
	s_branch .Lcv_tokens
; __device__ void conv_item(const Params& p, int it) {
;     ...
;     if (s >= 1) {
;       unpack8(*reinterpret_cast<const u32x4*>(p.Cb + o - 512), a);
;       unpack8(*reinterpret_cast<const u32x4*>(p.Hb + o - 512), b);
; #pragma unroll
;       for (int j = 0; j < 8; ++j) u1[j] = a[j] * b[j];
;     } else {
; #pragma unroll
;       for (int j = 0; j < 8; ++j) u1[j] = prompt ? 0.f : p.cache_conv[(size_t)(sb * 2 + 1) * 512 + c0 + j];
;     }
;     if (s >= 2) {
;       unpack8(*reinterpret_cast<const u32x4*>(p.Cb + o - 1024), a);
;       unpack8(*reinterpret_cast<const u32x4*>(p.Hb + o - 1024), b);
; #pragma unroll
;       for (int j = 0; j < 8; ++j) u2[j] = a[j] * b[j];
;     } else {
; #pragma unroll
;       for (int j = 0; j < 8; ++j) u2[j] = prompt ? 0.f : p.cache_conv[(size_t)(sb * 2 + s) * 512 + c0 + j];
;     }
;     unpack8(*reinterpret_cast<const u32x4*>(p.Bb + o), bg);
;     unpack8(*reinterpret_cast<const u32x4*>(p.Gb + (size_t)tok * 2048 + 1024 + c0), gt);
;     float z[8];
; #pragma unroll
;     for (int j = 0; j < 8; ++j) z[j] = bg[j] * (w0[j] * u2[j] + w1[j] * u1[j] + w2[j] * u0[j]) * gt[j];
;     u32x4 zo;
;     zo.x = pack2(z[0], z[1]); zo.y = pack2(z[2], z[3]); zo.z = pack2(z[4], z[5]); zo.w = pack2(z[6], z[7]);
;     *reinterpret_cast<u32x4*>(p.Xb + (size_t)tok * 2048 + 1024 + c0) = zo;
.Lcv_normal:
	s_waitcnt vmcnt(16)
	v_lshlrev_b32_e32 v240, 16, v24
	v_and_b32_e32 v241, 0xffff0000, v24
	v_lshlrev_b32_e32 v242, 16, v64
	v_and_b32_e32 v243, 0xffff0000, v64
	v_mul_f32_e32 v136, v240, v242
	v_mul_f32_e32 v137, v241, v243
	v_lshlrev_b32_e32 v240, 16, v25
	v_and_b32_e32 v241, 0xffff0000, v25
	v_lshlrev_b32_e32 v242, 16, v65
	v_and_b32_e32 v243, 0xffff0000, v65
	v_mul_f32_e32 v138, v240, v242
	v_mul_f32_e32 v139, v241, v243
	v_lshlrev_b32_e32 v240, 16, v26
	v_and_b32_e32 v241, 0xffff0000, v26
	v_lshlrev_b32_e32 v242, 16, v66
	v_and_b32_e32 v243, 0xffff0000, v66
	v_mul_f32_e32 v140, v240, v242
	v_mul_f32_e32 v141, v241, v243
	v_lshlrev_b32_e32 v240, 16, v27
	v_and_b32_e32 v241, 0xffff0000, v27
	v_lshlrev_b32_e32 v242, 16, v67
	v_and_b32_e32 v243, 0xffff0000, v67
	v_mul_f32_e32 v142, v240, v242
	v_mul_f32_e32 v143, v241, v243
	v_lshlrev_b32_e32 v240, 16, v28
	v_and_b32_e32 v241, 0xffff0000, v28
	v_lshlrev_b32_e32 v242, 16, v68
	v_and_b32_e32 v243, 0xffff0000, v68
	v_mul_f32_e32 v144, v240, v242
	v_mul_f32_e32 v145, v241, v243
	v_lshlrev_b32_e32 v240, 16, v29
	v_and_b32_e32 v241, 0xffff0000, v29
	v_lshlrev_b32_e32 v242, 16, v69
	v_and_b32_e32 v243, 0xffff0000, v69
	v_mul_f32_e32 v146, v240, v242
	v_mul_f32_e32 v147, v241, v243
	v_lshlrev_b32_e32 v240, 16, v30
	v_and_b32_e32 v241, 0xffff0000, v30
	v_lshlrev_b32_e32 v242, 16, v70
	v_and_b32_e32 v243, 0xffff0000, v70
	v_mul_f32_e32 v148, v240, v242
	v_mul_f32_e32 v149, v241, v243
	v_lshlrev_b32_e32 v240, 16, v31
	v_and_b32_e32 v241, 0xffff0000, v31
	v_lshlrev_b32_e32 v242, 16, v71
	v_and_b32_e32 v243, 0xffff0000, v71
	v_mul_f32_e32 v150, v240, v242
	v_mul_f32_e32 v151, v241, v243
.Lcv_tokens:
	v_lshl_add_u64 v[252:253], v[178:179], 0, v[246:247]
	s_mov_b32 s12, 0
	s_cmp_lt_u32 s9, 0x8000
	s_cbranch_scc0 .Lcv_odchk_s
	s_and_b32 s13, s9, 0x3fff
	s_cmp_eq_u32 s13, 0x3ff8
	s_cselect_b32 s12, 1, 0
	s_branch .Lcv_odchk_done
.Lcv_odchk_s:
	s_and_b32 s13, s9, 15
	s_cmp_eq_u32 s13, 8
	s_cselect_b32 s12, 2, 0
.Lcv_odchk_done:
	v_lshlrev_b32_e32 v240, 16, v32
	v_and_b32_e32 v241, 0xffff0000, v32
	v_lshlrev_b32_e32 v242, 16, v72
	v_and_b32_e32 v243, 0xffff0000, v72
	v_mul_f32_e32 v152, v240, v242
	v_mul_f32_e32 v153, v241, v243
	v_lshlrev_b32_e32 v240, 16, v33
	v_and_b32_e32 v241, 0xffff0000, v33
	v_lshlrev_b32_e32 v242, 16, v73
	v_and_b32_e32 v243, 0xffff0000, v73
	v_mul_f32_e32 v154, v240, v242
	v_mul_f32_e32 v155, v241, v243
	v_lshlrev_b32_e32 v240, 16, v34
	v_and_b32_e32 v241, 0xffff0000, v34
	v_lshlrev_b32_e32 v242, 16, v74
	v_and_b32_e32 v243, 0xffff0000, v74
	v_mul_f32_e32 v156, v240, v242
	v_mul_f32_e32 v157, v241, v243
	v_lshlrev_b32_e32 v240, 16, v35
	v_and_b32_e32 v241, 0xffff0000, v35
	v_lshlrev_b32_e32 v242, 16, v75
	v_and_b32_e32 v243, 0xffff0000, v75
	v_mul_f32_e32 v158, v240, v242
	v_mul_f32_e32 v159, v241, v243
	v_mul_f32_e32 v232, v4, v136
	v_mul_f32_e32 v233, v5, v137
	v_mul_f32_e32 v234, v6, v138
	v_mul_f32_e32 v235, v7, v139
	v_mul_f32_e32 v236, v0, v140
	v_mul_f32_e32 v237, v1, v141
	v_mul_f32_e32 v238, v2, v142
	v_mul_f32_e32 v239, v3, v143
	v_fmac_f32_e32 v232, v12, v144
	v_fmac_f32_e32 v233, v13, v145
	v_fmac_f32_e32 v234, v14, v146
	v_fmac_f32_e32 v235, v15, v147
	v_fmac_f32_e32 v236, v8, v148
	v_fmac_f32_e32 v237, v9, v149
	v_fmac_f32_e32 v238, v10, v150
	v_fmac_f32_e32 v239, v11, v151
	v_fmac_f32_e32 v232, v20, v152
	v_fmac_f32_e32 v233, v21, v153
	v_fmac_f32_e32 v234, v22, v154
	v_fmac_f32_e32 v235, v23, v155
	v_fmac_f32_e32 v236, v16, v156
	v_fmac_f32_e32 v237, v17, v157
	v_fmac_f32_e32 v238, v18, v158
	v_fmac_f32_e32 v239, v19, v159
	s_waitcnt vmcnt(8)
	v_lshlrev_b32_e32 v240, 16, v104
	v_and_b32_e32 v241, 0xffff0000, v104
	v_mul_f32_e32 v232, v232, v240
	v_mul_f32_e32 v233, v233, v241
	v_lshlrev_b32_e32 v240, 16, v105
	v_and_b32_e32 v241, 0xffff0000, v105
	v_mul_f32_e32 v234, v234, v240
	v_mul_f32_e32 v235, v235, v241
	v_lshlrev_b32_e32 v240, 16, v106
	v_and_b32_e32 v241, 0xffff0000, v106
	v_mul_f32_e32 v236, v236, v240
	v_mul_f32_e32 v237, v237, v241
	v_lshlrev_b32_e32 v240, 16, v107
	v_and_b32_e32 v241, 0xffff0000, v107
	v_mul_f32_e32 v238, v238, v240
	v_mul_f32_e32 v239, v239, v241
	s_waitcnt vmcnt(7)
	v_lshlrev_b32_e32 v240, 16, v200
	v_and_b32_e32 v241, 0xffff0000, v200
	v_mul_f32_e32 v232, v232, v240
	v_mul_f32_e32 v233, v233, v241
	v_lshlrev_b32_e32 v240, 16, v201
	v_and_b32_e32 v241, 0xffff0000, v201
	v_mul_f32_e32 v234, v234, v240
	v_mul_f32_e32 v235, v235, v241
	v_lshlrev_b32_e32 v240, 16, v202
	v_and_b32_e32 v241, 0xffff0000, v202
	v_mul_f32_e32 v236, v236, v240
	v_mul_f32_e32 v237, v237, v241
	v_lshlrev_b32_e32 v240, 16, v203
	v_and_b32_e32 v241, 0xffff0000, v203
	v_mul_f32_e32 v238, v238, v240
	v_mul_f32_e32 v239, v239, v241
	v_cvt_pk_bf16_f32 v244, v232, v233
	v_cvt_pk_bf16_f32 v245, v234, v235
	v_cvt_pk_bf16_f32 v246, v236, v237
	v_cvt_pk_bf16_f32 v247, v238, v239
	global_store_dwordx4 v[252:253], v[244:247], off offset:2048
	v_lshlrev_b32_e32 v240, 16, v36
	v_and_b32_e32 v241, 0xffff0000, v36
	v_lshlrev_b32_e32 v242, 16, v76
	v_and_b32_e32 v243, 0xffff0000, v76
	v_mul_f32_e32 v136, v240, v242
	v_mul_f32_e32 v137, v241, v243
	v_lshlrev_b32_e32 v240, 16, v37
	v_and_b32_e32 v241, 0xffff0000, v37
	v_lshlrev_b32_e32 v242, 16, v77
	v_and_b32_e32 v243, 0xffff0000, v77
	v_mul_f32_e32 v138, v240, v242
	v_mul_f32_e32 v139, v241, v243
	v_lshlrev_b32_e32 v240, 16, v38
	v_and_b32_e32 v241, 0xffff0000, v38
	v_lshlrev_b32_e32 v242, 16, v78
	v_and_b32_e32 v243, 0xffff0000, v78
	v_mul_f32_e32 v140, v240, v242
	v_mul_f32_e32 v141, v241, v243
	v_lshlrev_b32_e32 v240, 16, v39
	v_and_b32_e32 v241, 0xffff0000, v39
	v_lshlrev_b32_e32 v242, 16, v79
	v_and_b32_e32 v243, 0xffff0000, v79
	v_mul_f32_e32 v142, v240, v242
	v_mul_f32_e32 v143, v241, v243
	v_mul_f32_e32 v232, v4, v144
	v_mul_f32_e32 v233, v5, v145
	v_mul_f32_e32 v234, v6, v146
	v_mul_f32_e32 v235, v7, v147
	v_mul_f32_e32 v236, v0, v148
	v_mul_f32_e32 v237, v1, v149
	v_mul_f32_e32 v238, v2, v150
	v_mul_f32_e32 v239, v3, v151
	v_fmac_f32_e32 v232, v12, v152
	v_fmac_f32_e32 v233, v13, v153
	v_fmac_f32_e32 v234, v14, v154
	v_fmac_f32_e32 v235, v15, v155
	v_fmac_f32_e32 v236, v8, v156
	v_fmac_f32_e32 v237, v9, v157
	v_fmac_f32_e32 v238, v10, v158
	v_fmac_f32_e32 v239, v11, v159
	v_fmac_f32_e32 v232, v20, v136
	v_fmac_f32_e32 v233, v21, v137
	v_fmac_f32_e32 v234, v22, v138
	v_fmac_f32_e32 v235, v23, v139
	v_fmac_f32_e32 v236, v16, v140
	v_fmac_f32_e32 v237, v17, v141
	v_fmac_f32_e32 v238, v18, v142
	v_fmac_f32_e32 v239, v19, v143
	v_lshlrev_b32_e32 v240, 16, v108
	v_and_b32_e32 v241, 0xffff0000, v108
	v_mul_f32_e32 v232, v232, v240
	v_mul_f32_e32 v233, v233, v241
	v_lshlrev_b32_e32 v240, 16, v109
	v_and_b32_e32 v241, 0xffff0000, v109
	v_mul_f32_e32 v234, v234, v240
	v_mul_f32_e32 v235, v235, v241
	v_lshlrev_b32_e32 v240, 16, v110
	v_and_b32_e32 v241, 0xffff0000, v110
	v_mul_f32_e32 v236, v236, v240
	v_mul_f32_e32 v237, v237, v241
	v_lshlrev_b32_e32 v240, 16, v111
	v_and_b32_e32 v241, 0xffff0000, v111
	v_mul_f32_e32 v238, v238, v240
	v_mul_f32_e32 v239, v239, v241
	s_waitcnt vmcnt(7)
; __device__ void conv_item(const Params& p, int it) {
;     ...
;     if (s >= 2) {
;       unpack8(*reinterpret_cast<const u32x4*>(p.Cb + o - 1024), a);
;       unpack8(*reinterpret_cast<const u32x4*>(p.Hb + o - 1024), b);
; #pragma unroll
;       for (int j = 0; j < 8; ++j) u2[j] = a[j] * b[j];
;     } else {
; #pragma unroll
;       for (int j = 0; j < 8; ++j) u2[j] = prompt ? 0.f : p.cache_conv[(size_t)(sb * 2 + s) * 512 + c0 + j];
;     }
;     unpack8(*reinterpret_cast<const u32x4*>(p.Bb + o), bg);
;     unpack8(*reinterpret_cast<const u32x4*>(p.Gb + (size_t)tok * 2048 + 1024 + c0), gt);
;     float z[8];
; #pragma unroll
;     for (int j = 0; j < 8; ++j) z[j] = bg[j] * (w0[j] * u2[j] + w1[j] * u1[j] + w2[j] * u0[j]) * gt[j];
;     u32x4 zo;
;     zo.x = pack2(z[0], z[1]); zo.y = pack2(z[2], z[3]); zo.z = pack2(z[4], z[5]); zo.w = pack2(z[6], z[7]);
;     *reinterpret_cast<u32x4*>(p.Xb + (size_t)tok * 2048 + 1024 + c0) = zo;
	v_lshlrev_b32_e32 v240, 16, v204
	v_and_b32_e32 v241, 0xffff0000, v204
	v_mul_f32_e32 v232, v232, v240
	v_mul_f32_e32 v233, v233, v241
	v_lshlrev_b32_e32 v240, 16, v205
	v_and_b32_e32 v241, 0xffff0000, v205
	v_mul_f32_e32 v234, v234, v240
	v_mul_f32_e32 v235, v235, v241
	v_lshlrev_b32_e32 v240, 16, v206
	v_and_b32_e32 v241, 0xffff0000, v206
	v_mul_f32_e32 v236, v236, v240
	v_mul_f32_e32 v237, v237, v241
	v_lshlrev_b32_e32 v240, 16, v207
	v_and_b32_e32 v241, 0xffff0000, v207
	v_mul_f32_e32 v238, v238, v240
	v_mul_f32_e32 v239, v239, v241
	v_cvt_pk_bf16_f32 v244, v232, v233
	v_cvt_pk_bf16_f32 v245, v234, v235
	v_cvt_pk_bf16_f32 v246, v236, v237
	v_cvt_pk_bf16_f32 v247, v238, v239
	v_lshl_add_u64 v[252:253], v[252:253], 0, s[10:11]
	global_store_dwordx4 v[252:253], v[244:247], off offset:2048
	v_lshlrev_b32_e32 v240, 16, v40
	v_and_b32_e32 v241, 0xffff0000, v40
	v_lshlrev_b32_e32 v242, 16, v80
	v_and_b32_e32 v243, 0xffff0000, v80
	v_mul_f32_e32 v144, v240, v242
	v_mul_f32_e32 v145, v241, v243
	v_lshlrev_b32_e32 v240, 16, v41
	v_and_b32_e32 v241, 0xffff0000, v41
	v_lshlrev_b32_e32 v242, 16, v81
	v_and_b32_e32 v243, 0xffff0000, v81
	v_mul_f32_e32 v146, v240, v242
	v_mul_f32_e32 v147, v241, v243
	v_lshlrev_b32_e32 v240, 16, v42
	v_and_b32_e32 v241, 0xffff0000, v42
	v_lshlrev_b32_e32 v242, 16, v82
	v_and_b32_e32 v243, 0xffff0000, v82
	v_mul_f32_e32 v148, v240, v242
	v_mul_f32_e32 v149, v241, v243
	v_lshlrev_b32_e32 v240, 16, v43
	v_and_b32_e32 v241, 0xffff0000, v43
	v_lshlrev_b32_e32 v242, 16, v83
	v_and_b32_e32 v243, 0xffff0000, v83
	v_mul_f32_e32 v150, v240, v242
	v_mul_f32_e32 v151, v241, v243
	v_mul_f32_e32 v232, v4, v152
	v_mul_f32_e32 v233, v5, v153
	v_mul_f32_e32 v234, v6, v154
	v_mul_f32_e32 v235, v7, v155
	v_mul_f32_e32 v236, v0, v156
	v_mul_f32_e32 v237, v1, v157
	v_mul_f32_e32 v238, v2, v158
	v_mul_f32_e32 v239, v3, v159
	v_fmac_f32_e32 v232, v12, v136
	v_fmac_f32_e32 v233, v13, v137
	v_fmac_f32_e32 v234, v14, v138
	v_fmac_f32_e32 v235, v15, v139
	v_fmac_f32_e32 v236, v8, v140
	v_fmac_f32_e32 v237, v9, v141
	v_fmac_f32_e32 v238, v10, v142
	v_fmac_f32_e32 v239, v11, v143
	v_fmac_f32_e32 v232, v20, v144
	v_fmac_f32_e32 v233, v21, v145
	v_fmac_f32_e32 v234, v22, v146
	v_fmac_f32_e32 v235, v23, v147
	v_fmac_f32_e32 v236, v16, v148
	v_fmac_f32_e32 v237, v17, v149
	v_fmac_f32_e32 v238, v18, v150
	v_fmac_f32_e32 v239, v19, v151
	v_lshlrev_b32_e32 v240, 16, v112
	v_and_b32_e32 v241, 0xffff0000, v112
	v_mul_f32_e32 v232, v232, v240
	v_mul_f32_e32 v233, v233, v241
	v_lshlrev_b32_e32 v240, 16, v113
	v_and_b32_e32 v241, 0xffff0000, v113
	v_mul_f32_e32 v234, v234, v240
	v_mul_f32_e32 v235, v235, v241
	v_lshlrev_b32_e32 v240, 16, v114
	v_and_b32_e32 v241, 0xffff0000, v114
	v_mul_f32_e32 v236, v236, v240
	v_mul_f32_e32 v237, v237, v241
	v_lshlrev_b32_e32 v240, 16, v115
	v_and_b32_e32 v241, 0xffff0000, v115
	v_mul_f32_e32 v238, v238, v240
	v_mul_f32_e32 v239, v239, v241
	s_waitcnt vmcnt(7)
	v_lshlrev_b32_e32 v240, 16, v208
	v_and_b32_e32 v241, 0xffff0000, v208
	v_mul_f32_e32 v232, v232, v240
	v_mul_f32_e32 v233, v233, v241
	v_lshlrev_b32_e32 v240, 16, v209
	v_and_b32_e32 v241, 0xffff0000, v209
	v_mul_f32_e32 v234, v234, v240
	v_mul_f32_e32 v235, v235, v241
	v_lshlrev_b32_e32 v240, 16, v210
	v_and_b32_e32 v241, 0xffff0000, v210
	v_mul_f32_e32 v236, v236, v240
	v_mul_f32_e32 v237, v237, v241
	v_lshlrev_b32_e32 v240, 16, v211
	v_and_b32_e32 v241, 0xffff0000, v211
	v_mul_f32_e32 v238, v238, v240
	v_mul_f32_e32 v239, v239, v241
	v_cvt_pk_bf16_f32 v244, v232, v233
	v_cvt_pk_bf16_f32 v245, v234, v235
	v_cvt_pk_bf16_f32 v246, v236, v237
	v_cvt_pk_bf16_f32 v247, v238, v239
	v_lshl_add_u64 v[252:253], v[252:253], 0, s[10:11]
	global_store_dwordx4 v[252:253], v[244:247], off offset:2048
	v_lshlrev_b32_e32 v240, 16, v44
	v_and_b32_e32 v241, 0xffff0000, v44
	v_lshlrev_b32_e32 v242, 16, v84
	v_and_b32_e32 v243, 0xffff0000, v84
	v_mul_f32_e32 v152, v240, v242
	v_mul_f32_e32 v153, v241, v243
	v_lshlrev_b32_e32 v240, 16, v45
	v_and_b32_e32 v241, 0xffff0000, v45
	v_lshlrev_b32_e32 v242, 16, v85
	v_and_b32_e32 v243, 0xffff0000, v85
	v_mul_f32_e32 v154, v240, v242
	v_mul_f32_e32 v155, v241, v243
	v_lshlrev_b32_e32 v240, 16, v46
	v_and_b32_e32 v241, 0xffff0000, v46
	v_lshlrev_b32_e32 v242, 16, v86
	v_and_b32_e32 v243, 0xffff0000, v86
	v_mul_f32_e32 v156, v240, v242
	v_mul_f32_e32 v157, v241, v243
	v_lshlrev_b32_e32 v240, 16, v47
	v_and_b32_e32 v241, 0xffff0000, v47
	v_lshlrev_b32_e32 v242, 16, v87
	v_and_b32_e32 v243, 0xffff0000, v87
	v_mul_f32_e32 v158, v240, v242
	v_mul_f32_e32 v159, v241, v243
	v_mul_f32_e32 v232, v4, v136
	v_mul_f32_e32 v233, v5, v137
	v_mul_f32_e32 v234, v6, v138
	v_mul_f32_e32 v235, v7, v139
	v_mul_f32_e32 v236, v0, v140
	v_mul_f32_e32 v237, v1, v141
	v_mul_f32_e32 v238, v2, v142
	v_mul_f32_e32 v239, v3, v143
	v_fmac_f32_e32 v232, v12, v144
	v_fmac_f32_e32 v233, v13, v145
	v_fmac_f32_e32 v234, v14, v146
	v_fmac_f32_e32 v235, v15, v147
	v_fmac_f32_e32 v236, v8, v148
	v_fmac_f32_e32 v237, v9, v149
	v_fmac_f32_e32 v238, v10, v150
	v_fmac_f32_e32 v239, v11, v151
	v_fmac_f32_e32 v232, v20, v152
	v_fmac_f32_e32 v233, v21, v153
	v_fmac_f32_e32 v234, v22, v154
	v_fmac_f32_e32 v235, v23, v155
	v_fmac_f32_e32 v236, v16, v156
	v_fmac_f32_e32 v237, v17, v157
	v_fmac_f32_e32 v238, v18, v158
	v_fmac_f32_e32 v239, v19, v159
	v_lshlrev_b32_e32 v240, 16, v116
	v_and_b32_e32 v241, 0xffff0000, v116
	v_mul_f32_e32 v232, v232, v240
	v_mul_f32_e32 v233, v233, v241
	v_lshlrev_b32_e32 v240, 16, v117
	v_and_b32_e32 v241, 0xffff0000, v117
	v_mul_f32_e32 v234, v234, v240
	v_mul_f32_e32 v235, v235, v241
	v_lshlrev_b32_e32 v240, 16, v118
	v_and_b32_e32 v241, 0xffff0000, v118
	v_mul_f32_e32 v236, v236, v240
	v_mul_f32_e32 v237, v237, v241
	v_lshlrev_b32_e32 v240, 16, v119
	v_and_b32_e32 v241, 0xffff0000, v119
	v_mul_f32_e32 v238, v238, v240
	v_mul_f32_e32 v239, v239, v241
	s_waitcnt vmcnt(7)
; __device__ void conv_item(const Params& p, int it) {
;     ...
;     if (s >= 2) {
;       unpack8(*reinterpret_cast<const u32x4*>(p.Cb + o - 1024), a);
;       unpack8(*reinterpret_cast<const u32x4*>(p.Hb + o - 1024), b);
; #pragma unroll
;       for (int j = 0; j < 8; ++j) u2[j] = a[j] * b[j];
;     } else {
; #pragma unroll
;       for (int j = 0; j < 8; ++j) u2[j] = prompt ? 0.f : p.cache_conv[(size_t)(sb * 2 + s) * 512 + c0 + j];
;     }
;     unpack8(*reinterpret_cast<const u32x4*>(p.Bb + o), bg);
;     unpack8(*reinterpret_cast<const u32x4*>(p.Gb + (size_t)tok * 2048 + 1024 + c0), gt);
;     float z[8];
; #pragma unroll
;     for (int j = 0; j < 8; ++j) z[j] = bg[j] * (w0[j] * u2[j] + w1[j] * u1[j] + w2[j] * u0[j]) * gt[j];
;     u32x4 zo;
;     zo.x = pack2(z[0], z[1]); zo.y = pack2(z[2], z[3]); zo.z = pack2(z[4], z[5]); zo.w = pack2(z[6], z[7]);
;     *reinterpret_cast<u32x4*>(p.Xb + (size_t)tok * 2048 + 1024 + c0) = zo;
	v_lshlrev_b32_e32 v240, 16, v212
	v_and_b32_e32 v241, 0xffff0000, v212
	v_mul_f32_e32 v232, v232, v240
	v_mul_f32_e32 v233, v233, v241
	v_lshlrev_b32_e32 v240, 16, v213
	v_and_b32_e32 v241, 0xffff0000, v213
	v_mul_f32_e32 v234, v234, v240
	v_mul_f32_e32 v235, v235, v241
	v_lshlrev_b32_e32 v240, 16, v214
	v_and_b32_e32 v241, 0xffff0000, v214
	v_mul_f32_e32 v236, v236, v240
	v_mul_f32_e32 v237, v237, v241
	v_lshlrev_b32_e32 v240, 16, v215
	v_and_b32_e32 v241, 0xffff0000, v215
	v_mul_f32_e32 v238, v238, v240
	v_mul_f32_e32 v239, v239, v241
	v_cvt_pk_bf16_f32 v244, v232, v233
	v_cvt_pk_bf16_f32 v245, v234, v235
	v_cvt_pk_bf16_f32 v246, v236, v237
	v_cvt_pk_bf16_f32 v247, v238, v239
	v_lshl_add_u64 v[252:253], v[252:253], 0, s[10:11]
	global_store_dwordx4 v[252:253], v[244:247], off offset:2048
	v_lshlrev_b32_e32 v240, 16, v48
	v_and_b32_e32 v241, 0xffff0000, v48
	v_lshlrev_b32_e32 v242, 16, v88
	v_and_b32_e32 v243, 0xffff0000, v88
	v_mul_f32_e32 v136, v240, v242
	v_mul_f32_e32 v137, v241, v243
	v_lshlrev_b32_e32 v240, 16, v49
	v_and_b32_e32 v241, 0xffff0000, v49
	v_lshlrev_b32_e32 v242, 16, v89
	v_and_b32_e32 v243, 0xffff0000, v89
	v_mul_f32_e32 v138, v240, v242
	v_mul_f32_e32 v139, v241, v243
	v_lshlrev_b32_e32 v240, 16, v50
	v_and_b32_e32 v241, 0xffff0000, v50
	v_lshlrev_b32_e32 v242, 16, v90
	v_and_b32_e32 v243, 0xffff0000, v90
	v_mul_f32_e32 v140, v240, v242
	v_mul_f32_e32 v141, v241, v243
	v_lshlrev_b32_e32 v240, 16, v51
	v_and_b32_e32 v241, 0xffff0000, v51
	v_lshlrev_b32_e32 v242, 16, v91
	v_and_b32_e32 v243, 0xffff0000, v91
	v_mul_f32_e32 v142, v240, v242
	v_mul_f32_e32 v143, v241, v243
	v_mul_f32_e32 v232, v4, v144
	v_mul_f32_e32 v233, v5, v145
	v_mul_f32_e32 v234, v6, v146
	v_mul_f32_e32 v235, v7, v147
	v_mul_f32_e32 v236, v0, v148
	v_mul_f32_e32 v237, v1, v149
	v_mul_f32_e32 v238, v2, v150
	v_mul_f32_e32 v239, v3, v151
	v_fmac_f32_e32 v232, v12, v152
	v_fmac_f32_e32 v233, v13, v153
	v_fmac_f32_e32 v234, v14, v154
	v_fmac_f32_e32 v235, v15, v155
	v_fmac_f32_e32 v236, v8, v156
	v_fmac_f32_e32 v237, v9, v157
	v_fmac_f32_e32 v238, v10, v158
	v_fmac_f32_e32 v239, v11, v159
	v_fmac_f32_e32 v232, v20, v136
	v_fmac_f32_e32 v233, v21, v137
	v_fmac_f32_e32 v234, v22, v138
	v_fmac_f32_e32 v235, v23, v139
	v_fmac_f32_e32 v236, v16, v140
	v_fmac_f32_e32 v237, v17, v141
	v_fmac_f32_e32 v238, v18, v142
	v_fmac_f32_e32 v239, v19, v143
	v_lshlrev_b32_e32 v240, 16, v120
	v_and_b32_e32 v241, 0xffff0000, v120
	v_mul_f32_e32 v232, v232, v240
	v_mul_f32_e32 v233, v233, v241
	v_lshlrev_b32_e32 v240, 16, v121
	v_and_b32_e32 v241, 0xffff0000, v121
	v_mul_f32_e32 v234, v234, v240
	v_mul_f32_e32 v235, v235, v241
	v_lshlrev_b32_e32 v240, 16, v122
	v_and_b32_e32 v241, 0xffff0000, v122
	v_mul_f32_e32 v236, v236, v240
	v_mul_f32_e32 v237, v237, v241
	v_lshlrev_b32_e32 v240, 16, v123
	v_and_b32_e32 v241, 0xffff0000, v123
	v_mul_f32_e32 v238, v238, v240
	v_mul_f32_e32 v239, v239, v241
	s_waitcnt vmcnt(7)
	v_lshlrev_b32_e32 v240, 16, v216
	v_and_b32_e32 v241, 0xffff0000, v216
	v_mul_f32_e32 v232, v232, v240
	v_mul_f32_e32 v233, v233, v241
	v_lshlrev_b32_e32 v240, 16, v217
	v_and_b32_e32 v241, 0xffff0000, v217
	v_mul_f32_e32 v234, v234, v240
	v_mul_f32_e32 v235, v235, v241
	v_lshlrev_b32_e32 v240, 16, v218
	v_and_b32_e32 v241, 0xffff0000, v218
	v_mul_f32_e32 v236, v236, v240
	v_mul_f32_e32 v237, v237, v241
	v_lshlrev_b32_e32 v240, 16, v219
	v_and_b32_e32 v241, 0xffff0000, v219
	v_mul_f32_e32 v238, v238, v240
	v_mul_f32_e32 v239, v239, v241
	v_cvt_pk_bf16_f32 v244, v232, v233
	v_cvt_pk_bf16_f32 v245, v234, v235
	v_cvt_pk_bf16_f32 v246, v236, v237
	v_cvt_pk_bf16_f32 v247, v238, v239
	v_lshl_add_u64 v[252:253], v[252:253], 0, s[10:11]
	global_store_dwordx4 v[252:253], v[244:247], off offset:2048
	v_lshlrev_b32_e32 v240, 16, v52
	v_and_b32_e32 v241, 0xffff0000, v52
	v_lshlrev_b32_e32 v242, 16, v92
	v_and_b32_e32 v243, 0xffff0000, v92
	v_mul_f32_e32 v144, v240, v242
	v_mul_f32_e32 v145, v241, v243
	v_lshlrev_b32_e32 v240, 16, v53
	v_and_b32_e32 v241, 0xffff0000, v53
	v_lshlrev_b32_e32 v242, 16, v93
	v_and_b32_e32 v243, 0xffff0000, v93
	v_mul_f32_e32 v146, v240, v242
	v_mul_f32_e32 v147, v241, v243
	v_lshlrev_b32_e32 v240, 16, v54
	v_and_b32_e32 v241, 0xffff0000, v54
	v_lshlrev_b32_e32 v242, 16, v94
	v_and_b32_e32 v243, 0xffff0000, v94
	v_mul_f32_e32 v148, v240, v242
	v_mul_f32_e32 v149, v241, v243
	v_lshlrev_b32_e32 v240, 16, v55
	v_and_b32_e32 v241, 0xffff0000, v55
	v_lshlrev_b32_e32 v242, 16, v95
	v_and_b32_e32 v243, 0xffff0000, v95
	v_mul_f32_e32 v150, v240, v242
	v_mul_f32_e32 v151, v241, v243
	v_mul_f32_e32 v232, v4, v152
	v_mul_f32_e32 v233, v5, v153
	v_mul_f32_e32 v234, v6, v154
	v_mul_f32_e32 v235, v7, v155
	v_mul_f32_e32 v236, v0, v156
	v_mul_f32_e32 v237, v1, v157
	v_mul_f32_e32 v238, v2, v158
	v_mul_f32_e32 v239, v3, v159
	v_fmac_f32_e32 v232, v12, v136
	v_fmac_f32_e32 v233, v13, v137
	v_fmac_f32_e32 v234, v14, v138
	v_fmac_f32_e32 v235, v15, v139
	v_fmac_f32_e32 v236, v8, v140
	v_fmac_f32_e32 v237, v9, v141
	v_fmac_f32_e32 v238, v10, v142
	v_fmac_f32_e32 v239, v11, v143
	v_fmac_f32_e32 v232, v20, v144
	v_fmac_f32_e32 v233, v21, v145
	v_fmac_f32_e32 v234, v22, v146
	v_fmac_f32_e32 v235, v23, v147
	v_fmac_f32_e32 v236, v16, v148
	v_fmac_f32_e32 v237, v17, v149
	v_fmac_f32_e32 v238, v18, v150
	v_fmac_f32_e32 v239, v19, v151
	v_lshlrev_b32_e32 v240, 16, v124
	v_and_b32_e32 v241, 0xffff0000, v124
	v_mul_f32_e32 v232, v232, v240
	v_mul_f32_e32 v233, v233, v241
	v_lshlrev_b32_e32 v240, 16, v125
	v_and_b32_e32 v241, 0xffff0000, v125
	v_mul_f32_e32 v234, v234, v240
	v_mul_f32_e32 v235, v235, v241
	v_lshlrev_b32_e32 v240, 16, v126
	v_and_b32_e32 v241, 0xffff0000, v126
	v_mul_f32_e32 v236, v236, v240
	v_mul_f32_e32 v237, v237, v241
	v_lshlrev_b32_e32 v240, 16, v127
	v_and_b32_e32 v241, 0xffff0000, v127
	v_mul_f32_e32 v238, v238, v240
	v_mul_f32_e32 v239, v239, v241
	s_waitcnt vmcnt(7)
; __device__ void conv_item(const Params& p, int it) {
;     ...
;     for (int j = 0; j < 8; ++j) u0[j] = a[j] * b[j];
;     const bool prompt = tok < NPROMPT;
;     const int s = prompt ? (tok & (SEQ - 1)) : ((tok - NPROMPT) & 15);
;     const int sb = prompt ? 0 : ((tok - NPROMPT) >> 4);
;     if (s >= 1) {
;       unpack8(*reinterpret_cast<const u32x4*>(p.Cb + o - 512), a);
;       unpack8(*reinterpret_cast<const u32x4*>(p.Hb + o - 512), b);
; #pragma unroll
;       for (int j = 0; j < 8; ++j) u1[j] = a[j] * b[j];
;     } else {
; #pragma unroll
;       for (int j = 0; j < 8; ++j) u1[j] = prompt ? 0.f : p.cache_conv[(size_t)(sb * 2 + 1) * 512 + c0 + j];
;     }
;     if (s >= 2) {
;       unpack8(*reinterpret_cast<const u32x4*>(p.Cb + o - 1024), a);
;       unpack8(*reinterpret_cast<const u32x4*>(p.Hb + o - 1024), b);
; #pragma unroll
;       for (int j = 0; j < 8; ++j) u2[j] = a[j] * b[j];
;     } else {
; #pragma unroll
;       for (int j = 0; j < 8; ++j) u2[j] = prompt ? 0.f : p.cache_conv[(size_t)(sb * 2 + s) * 512 + c0 + j];
;     }
;     unpack8(*reinterpret_cast<const u32x4*>(p.Bb + o), bg);
;     unpack8(*reinterpret_cast<const u32x4*>(p.Gb + (size_t)tok * 2048 + 1024 + c0), gt);
;     float z[8];
; #pragma unroll
;     for (int j = 0; j < 8; ++j) z[j] = bg[j] * (w0[j] * u2[j] + w1[j] * u1[j] + w2[j] * u0[j]) * gt[j];
;     u32x4 zo;
;     zo.x = pack2(z[0], z[1]); zo.y = pack2(z[2], z[3]); zo.z = pack2(z[4], z[5]); zo.w = pack2(z[6], z[7]);
;     *reinterpret_cast<u32x4*>(p.Xb + (size_t)tok * 2048 + 1024 + c0) = zo;
;     float* od = nullptr;
;     if (prompt) { if (s >= SEQ - 2) od = p.out + O_CP + (size_t)((tok >> 14) * 2 + (s - (SEQ - 2))) * 512 + c0; }
;     else { if (s >= 14) od = p.out + O_CS + (size_t)(sb * 2 + (s - 14)) * 512 + c0; }
;     if (od != nullptr) {
; #pragma unroll
;       for (int j = 0; j < 8; ++j) od[j] = u0[j];
	v_lshlrev_b32_e32 v240, 16, v220
	v_and_b32_e32 v241, 0xffff0000, v220
	v_mul_f32_e32 v232, v232, v240
	v_mul_f32_e32 v233, v233, v241
	v_lshlrev_b32_e32 v240, 16, v221
	v_and_b32_e32 v241, 0xffff0000, v221
	v_mul_f32_e32 v234, v234, v240
	v_mul_f32_e32 v235, v235, v241
	v_lshlrev_b32_e32 v240, 16, v222
	v_and_b32_e32 v241, 0xffff0000, v222
	v_mul_f32_e32 v236, v236, v240
	v_mul_f32_e32 v237, v237, v241
	v_lshlrev_b32_e32 v240, 16, v223
	v_and_b32_e32 v241, 0xffff0000, v223
	v_mul_f32_e32 v238, v238, v240
	v_mul_f32_e32 v239, v239, v241
	v_cvt_pk_bf16_f32 v244, v232, v233
	v_cvt_pk_bf16_f32 v245, v234, v235
	v_cvt_pk_bf16_f32 v246, v236, v237
	v_cvt_pk_bf16_f32 v247, v238, v239
	v_lshl_add_u64 v[252:253], v[252:253], 0, s[10:11]
	global_store_dwordx4 v[252:253], v[244:247], off offset:2048
	v_lshlrev_b32_e32 v240, 16, v56
	v_and_b32_e32 v241, 0xffff0000, v56
	v_lshlrev_b32_e32 v242, 16, v96
	v_and_b32_e32 v243, 0xffff0000, v96
	v_mul_f32_e32 v152, v240, v242
	v_mul_f32_e32 v153, v241, v243
	v_lshlrev_b32_e32 v240, 16, v57
	v_and_b32_e32 v241, 0xffff0000, v57
	v_lshlrev_b32_e32 v242, 16, v97
	v_and_b32_e32 v243, 0xffff0000, v97
	v_mul_f32_e32 v154, v240, v242
	v_mul_f32_e32 v155, v241, v243
	v_lshlrev_b32_e32 v240, 16, v58
	v_and_b32_e32 v241, 0xffff0000, v58
	v_lshlrev_b32_e32 v242, 16, v98
	v_and_b32_e32 v243, 0xffff0000, v98
	v_mul_f32_e32 v156, v240, v242
	v_mul_f32_e32 v157, v241, v243
	v_lshlrev_b32_e32 v240, 16, v59
	v_and_b32_e32 v241, 0xffff0000, v59
	v_lshlrev_b32_e32 v242, 16, v99
	v_and_b32_e32 v243, 0xffff0000, v99
	v_mul_f32_e32 v158, v240, v242
	v_mul_f32_e32 v159, v241, v243
	v_mul_f32_e32 v232, v4, v136
	v_mul_f32_e32 v233, v5, v137
	v_mul_f32_e32 v234, v6, v138
	v_mul_f32_e32 v235, v7, v139
	v_mul_f32_e32 v236, v0, v140
	v_mul_f32_e32 v237, v1, v141
	v_mul_f32_e32 v238, v2, v142
	v_mul_f32_e32 v239, v3, v143
	v_fmac_f32_e32 v232, v12, v144
	v_fmac_f32_e32 v233, v13, v145
	v_fmac_f32_e32 v234, v14, v146
	v_fmac_f32_e32 v235, v15, v147
	v_fmac_f32_e32 v236, v8, v148
	v_fmac_f32_e32 v237, v9, v149
	v_fmac_f32_e32 v238, v10, v150
	v_fmac_f32_e32 v239, v11, v151
	v_fmac_f32_e32 v232, v20, v152
	v_fmac_f32_e32 v233, v21, v153
	v_fmac_f32_e32 v234, v22, v154
	v_fmac_f32_e32 v235, v23, v155
	v_fmac_f32_e32 v236, v16, v156
	v_fmac_f32_e32 v237, v17, v157
	v_fmac_f32_e32 v238, v18, v158
	v_fmac_f32_e32 v239, v19, v159
	v_lshlrev_b32_e32 v240, 16, v128
	v_and_b32_e32 v241, 0xffff0000, v128
	v_mul_f32_e32 v232, v232, v240
	v_mul_f32_e32 v233, v233, v241
	v_lshlrev_b32_e32 v240, 16, v129
	v_and_b32_e32 v241, 0xffff0000, v129
	v_mul_f32_e32 v234, v234, v240
	v_mul_f32_e32 v235, v235, v241
	v_lshlrev_b32_e32 v240, 16, v130
	v_and_b32_e32 v241, 0xffff0000, v130
	v_mul_f32_e32 v236, v236, v240
	v_mul_f32_e32 v237, v237, v241
	v_lshlrev_b32_e32 v240, 16, v131
	v_and_b32_e32 v241, 0xffff0000, v131
	v_mul_f32_e32 v238, v238, v240
	v_mul_f32_e32 v239, v239, v241
	s_waitcnt vmcnt(7)
	v_lshlrev_b32_e32 v240, 16, v224
	v_and_b32_e32 v241, 0xffff0000, v224
	v_mul_f32_e32 v232, v232, v240
	v_mul_f32_e32 v233, v233, v241
	v_lshlrev_b32_e32 v240, 16, v225
	v_and_b32_e32 v241, 0xffff0000, v225
	v_mul_f32_e32 v234, v234, v240
	v_mul_f32_e32 v235, v235, v241
	v_lshlrev_b32_e32 v240, 16, v226
	v_and_b32_e32 v241, 0xffff0000, v226
	v_mul_f32_e32 v236, v236, v240
	v_mul_f32_e32 v237, v237, v241
	v_lshlrev_b32_e32 v240, 16, v227
	v_and_b32_e32 v241, 0xffff0000, v227
	v_mul_f32_e32 v238, v238, v240
	v_mul_f32_e32 v239, v239, v241
	v_cvt_pk_bf16_f32 v244, v232, v233
	v_cvt_pk_bf16_f32 v245, v234, v235
	v_cvt_pk_bf16_f32 v246, v236, v237
	v_cvt_pk_bf16_f32 v247, v238, v239
	v_lshl_add_u64 v[252:253], v[252:253], 0, s[10:11]
	global_store_dwordx4 v[252:253], v[244:247], off offset:2048
	s_cmp_eq_u32 s12, 0
	s_cbranch_scc1 .Lcv_od_skip6
	s_cmp_eq_u32 s12, 1
	s_cbranch_scc0 .Lcv_od_s6
	s_lshr_b32 s13, s9, 14
	s_lshl_b32 s13, s13, 12
	v_mov_b32_e32 v240, s13
	v_mov_b32_e32 v241, 0
	v_lshl_add_u64 v[240:241], v[174:175], 0, v[240:241]
	s_branch .Lcv_od_st6
; __device__ void conv_item(const Params& p, int it) {
;     ...
;     for (int j = 0; j < 8; ++j) z[j] = bg[j] * (w0[j] * u2[j] + w1[j] * u1[j] + w2[j] * u0[j]) * gt[j];
;     u32x4 zo;
;     zo.x = pack2(z[0], z[1]); zo.y = pack2(z[2], z[3]); zo.z = pack2(z[4], z[5]); zo.w = pack2(z[6], z[7]);
;     *reinterpret_cast<u32x4*>(p.Xb + (size_t)tok * 2048 + 1024 + c0) = zo;
;     float* od = nullptr;
;     if (prompt) { if (s >= SEQ - 2) od = p.out + O_CP + (size_t)((tok >> 14) * 2 + (s - (SEQ - 2))) * 512 + c0; }
;     else { if (s >= 14) od = p.out + O_CS + (size_t)(sb * 2 + (s - 14)) * 512 + c0; }
;     if (od != nullptr) {
; #pragma unroll
;       for (int j = 0; j < 8; ++j) od[j] = u0[j];
.Lcv_od_s6:
	s_sub_i32 s13, s9, 0x8000
	s_lshr_b32 s13, s13, 4
	s_lshl_b32 s13, s13, 12
	v_mov_b32_e32 v240, s13
	v_mov_b32_e32 v241, 0
	v_lshl_add_u64 v[240:241], v[172:173], 0, v[240:241]
.Lcv_od_st6:
	global_store_dwordx4 v[240:241], v[152:155], off
	global_store_dwordx4 v[240:241], v[156:159], off offset:16
.Lcv_od_skip6:
	v_lshlrev_b32_e32 v240, 16, v60
	v_and_b32_e32 v241, 0xffff0000, v60
	v_lshlrev_b32_e32 v242, 16, v100
	v_and_b32_e32 v243, 0xffff0000, v100
	v_mul_f32_e32 v136, v240, v242
	v_mul_f32_e32 v137, v241, v243
	v_lshlrev_b32_e32 v240, 16, v61
	v_and_b32_e32 v241, 0xffff0000, v61
	v_lshlrev_b32_e32 v242, 16, v101
	v_and_b32_e32 v243, 0xffff0000, v101
	v_mul_f32_e32 v138, v240, v242
	v_mul_f32_e32 v139, v241, v243
	v_lshlrev_b32_e32 v240, 16, v62
	v_and_b32_e32 v241, 0xffff0000, v62
	v_lshlrev_b32_e32 v242, 16, v102
	v_and_b32_e32 v243, 0xffff0000, v102
	v_mul_f32_e32 v140, v240, v242
	v_mul_f32_e32 v141, v241, v243
	v_lshlrev_b32_e32 v240, 16, v63
	v_and_b32_e32 v241, 0xffff0000, v63
	v_lshlrev_b32_e32 v242, 16, v103
	v_and_b32_e32 v243, 0xffff0000, v103
	v_mul_f32_e32 v142, v240, v242
	v_mul_f32_e32 v143, v241, v243
	v_mul_f32_e32 v232, v4, v144
	v_mul_f32_e32 v233, v5, v145
	v_mul_f32_e32 v234, v6, v146
	v_mul_f32_e32 v235, v7, v147
	v_mul_f32_e32 v236, v0, v148
	v_mul_f32_e32 v237, v1, v149
	v_mul_f32_e32 v238, v2, v150
	v_mul_f32_e32 v239, v3, v151
	v_fmac_f32_e32 v232, v12, v152
	v_fmac_f32_e32 v233, v13, v153
	v_fmac_f32_e32 v234, v14, v154
	v_fmac_f32_e32 v235, v15, v155
	v_fmac_f32_e32 v236, v8, v156
	v_fmac_f32_e32 v237, v9, v157
	v_fmac_f32_e32 v238, v10, v158
	v_fmac_f32_e32 v239, v11, v159
	v_fmac_f32_e32 v232, v20, v136
	v_fmac_f32_e32 v233, v21, v137
	v_fmac_f32_e32 v234, v22, v138
	v_fmac_f32_e32 v235, v23, v139
	v_fmac_f32_e32 v236, v16, v140
	v_fmac_f32_e32 v237, v17, v141
	v_fmac_f32_e32 v238, v18, v142
	v_fmac_f32_e32 v239, v19, v143
	v_lshlrev_b32_e32 v240, 16, v132
	v_and_b32_e32 v241, 0xffff0000, v132
	v_mul_f32_e32 v232, v232, v240
	v_mul_f32_e32 v233, v233, v241
	v_lshlrev_b32_e32 v240, 16, v133
	v_and_b32_e32 v241, 0xffff0000, v133
	v_mul_f32_e32 v234, v234, v240
	v_mul_f32_e32 v235, v235, v241
	v_lshlrev_b32_e32 v240, 16, v134
	v_and_b32_e32 v241, 0xffff0000, v134
	v_mul_f32_e32 v236, v236, v240
	v_mul_f32_e32 v237, v237, v241
	v_lshlrev_b32_e32 v240, 16, v135
	v_and_b32_e32 v241, 0xffff0000, v135
	v_mul_f32_e32 v238, v238, v240
	v_mul_f32_e32 v239, v239, v241
	s_waitcnt vmcnt(7)
	v_lshlrev_b32_e32 v240, 16, v228
	v_and_b32_e32 v241, 0xffff0000, v228
	v_mul_f32_e32 v232, v232, v240
	v_mul_f32_e32 v233, v233, v241
	v_lshlrev_b32_e32 v240, 16, v229
	v_and_b32_e32 v241, 0xffff0000, v229
	v_mul_f32_e32 v234, v234, v240
	v_mul_f32_e32 v235, v235, v241
	v_lshlrev_b32_e32 v240, 16, v230
	v_and_b32_e32 v241, 0xffff0000, v230
	v_mul_f32_e32 v236, v236, v240
	v_mul_f32_e32 v237, v237, v241
	v_lshlrev_b32_e32 v240, 16, v231
	v_and_b32_e32 v241, 0xffff0000, v231
	v_mul_f32_e32 v238, v238, v240
	v_mul_f32_e32 v239, v239, v241
	v_cvt_pk_bf16_f32 v244, v232, v233
	v_cvt_pk_bf16_f32 v245, v234, v235
	v_cvt_pk_bf16_f32 v246, v236, v237
	v_cvt_pk_bf16_f32 v247, v238, v239
	v_lshl_add_u64 v[252:253], v[252:253], 0, s[10:11]
	global_store_dwordx4 v[252:253], v[244:247], off offset:2048
	s_cmp_eq_u32 s12, 0
	s_cbranch_scc1 .Lcv_od_skip7
	s_cmp_eq_u32 s12, 1
	s_cbranch_scc0 .Lcv_od_s7
	s_lshr_b32 s13, s9, 14
	s_lshl_b32 s13, s13, 12
	s_add_i32 s13, s13, 0x800
	v_mov_b32_e32 v240, s13
	v_mov_b32_e32 v241, 0
	v_lshl_add_u64 v[240:241], v[174:175], 0, v[240:241]
	s_branch .Lcv_od_st7
.Lcv_od_s7:
	s_sub_i32 s13, s9, 0x8000
	s_lshr_b32 s13, s13, 4
	s_lshl_b32 s13, s13, 12
	s_add_i32 s13, s13, 0x800
	v_mov_b32_e32 v240, s13
	v_mov_b32_e32 v241, 0
	v_lshl_add_u64 v[240:241], v[172:173], 0, v[240:241]
.Lcv_od_st7:
	global_store_dwordx4 v[240:241], v[136:139], off
	global_store_dwordx4 v[240:241], v[140:143], off offset:16
.Lcv_od_skip7:
.LBB0_515:
	s_mov_b64 s[8:9], 0
